# attention item prologue rewritten: all global loads of the item in flight together, shared bpermute rounds
# baseline (speedup 1.0000x reference)
; __device__ __forceinline__ float bflo(unsigned u) { return __uint_as_float(u << 16); }
; __device__ __forceinline__ float bfhi(unsigned u) { return __uint_as_float(u & 0xffff0000u); }
; __device__ __forceinline__ void attn_item(LAS unsigned char* lds, const bf16* P, bf16* Y, const float* qg, const float* kg, const float* sinks, int item, int tid) {
;     ...
;     { const int w_ = tid >> 6, ln = tid & 63; const bf16* qp = P + (size_t)(R0 + (w_ & 1) * 64 + (ln & 15)) * PP + (hkv * 4 + (w_ >> 1)) * 64 + 8 * (ln >> 4);
; #pragma unroll
;       for (int it = 0; it < 4; ++it) { qraw[it][0] = *(const v4u*)(qp + (size_t)(16 * it) * PP); qraw[it][1] = *(const v4u*)(qp + (size_t)(16 * it) * PP + 32); } }
; #pragma unroll
;     for (int i = 0; i < 4; ++i) {
;         const int task = tid + 512 * i, key = task >> 3, c = task & 7; const bool ok = (nb > 0) || (key >= 128);
;         v4u kr = {0u, 0u, 0u, 0u}, vr = {0u, 0u, 0u, 0u};
;         if (ok) { const bf16* rp = P + (size_t)(R0 - 128 + key) * PP + hkv * 64 + 8 * c; kr = *(const v4u*)(rp + C_K); vr = *(const v4u*)(rp + C_V); }
;         float kf[8];
; #pragma unroll
;         for (int e = 0; e < 4; ++e) { kf[2 * e] = bflo(kr[e]); kf[2 * e + 1] = bfhi(kr[e]); }
;         float ss = 0.f;
; #pragma unroll
;         for (int e = 0; e < 8; ++e) ss += kf[e] * kf[e];
;         ss += __shfl_xor(ss, 1); ss += __shfl_xor(ss, 2); ss += __shfl_xor(ss, 4);
;         const float rs = rsqrtf(ss * (1.f / 64.f) + EPS);
.LBB0_132:
	s_andn2_b64 vcc, exec, s[18:19]
	s_cbranch_vccnz .LBB0_129
	s_bfe_u32 s3, s25, 0x40001
	s_lshl_b32 s22, s25, 6
	s_and_b32 s18, s22, 0xfffff800
	s_lshl_b32 s19, s3, 7
	s_and_b32 s2, s25, 1
	s_or_b32 s23, s19, s18
	v_or_b32_e32 v3, s23, v191
	v_mov_b64_e32 v[0:1], s[16:17]
	v_lshl_add_u32 v46, s2, 2, v192
	v_mad_i64_i32 v[4:5], s[18:19], v3, s36, v[0:1]
	v_lshlrev_b32_e32 v0, 6, v46
	v_ashrrev_i32_e32 v1, 31, v0
	v_lshl_add_u64 v[4:5], v[0:1], 1, v[4:5]
	v_mov_b32_e32 v123, v2
	v_lshl_add_u64 v[20:21], v[4:5], 0, v[122:123]
	global_load_dwordx4 v[160:163], v[104:105], off offset:16
	global_load_dwordx4 v[164:167], v[104:105], off
	v_ashrrev_i32_e32 v47, 31, v46
	v_lshl_add_u64 v[36:37], v[46:47], 2, s[42:43]
	global_load_dword v184, v[36:37], off
	global_load_dwordx4 v[168:171], v[108:109], off
	global_load_dwordx4 v[172:175], v[108:109], off offset:16
	global_load_dwordx4 v[176:179], v[108:109], off offset:128
	global_load_dwordx4 v[180:183], v[108:109], off offset:144
	s_mov_b32 s18, 0x17000
	v_add_co_u32_e32 v8, vcc, s18, v20
	s_mov_b32 s18, 0x2e000
	s_nop 0
	v_addc_co_u32_e32 v9, vcc, 0, v21, vcc
	v_add_co_u32_e32 v16, vcc, s18, v20
	s_mov_b32 s18, 0x45000
	s_nop 0
	v_addc_co_u32_e32 v17, vcc, 0, v21, vcc
	v_add_co_u32_e32 v24, vcc, s18, v20
	global_load_dwordx4 v[32:35], v[20:21], off
	global_load_dwordx4 v[28:31], v[20:21], off offset:64
	v_addc_co_u32_e32 v25, vcc, 0, v21, vcc
	global_load_dwordx4 v[4:7], v[8:9], off
	s_nop 0
	global_load_dwordx4 v[8:11], v[8:9], off offset:64
	s_nop 0
	global_load_dwordx4 v[12:15], v[16:17], off
	s_nop 0
	global_load_dwordx4 v[16:19], v[16:17], off offset:64
	s_nop 0
	global_load_dwordx4 v[20:23], v[24:25], off
	s_nop 0
	global_load_dwordx4 v[24:27], v[24:25], off offset:64
	v_readlane_b32 s18, v254, 31
	s_cmp_lg_u32 s3, 0
	v_readlane_b32 s19, v254, 32
	s_cselect_b64 s[44:45], -1, 0
	s_mov_b32 s29, s19
	s_lshl_b32 s28, s2, 7
	v_writelane_b32 v254, s18, 31
	s_addk_i32 s23, 0xff80
	v_lshl_add_u64 v[48:49], v[106:107], 0, s[28:29]
	v_writelane_b32 v254, s19, 32
	s_or_b64 s[28:29], s[64:65], s[44:45]
	v_mov_b32_e32 v64, 0
	v_mov_b32_e32 v65, 0
	v_mov_b32_e32 v66, 0
	v_mov_b32_e32 v67, 0
	v_mov_b32_e32 v68, 0
	v_mov_b32_e32 v69, 0
	v_mov_b32_e32 v70, 0
	v_mov_b32_e32 v71, 0
	v_mov_b32_e32 v76, 0
	v_mov_b32_e32 v77, 0
	v_mov_b32_e32 v78, 0
	v_mov_b32_e32 v79, 0
	v_mov_b32_e32 v80, 0
	v_mov_b32_e32 v81, 0
	v_mov_b32_e32 v82, 0
	v_mov_b32_e32 v83, 0
	v_mov_b32_e32 v84, 0
	v_mov_b32_e32 v85, 0
	v_mov_b32_e32 v86, 0
	v_mov_b32_e32 v87, 0
	v_mov_b32_e32 v88, 0
	v_mov_b32_e32 v89, 0
	v_mov_b32_e32 v90, 0
	v_mov_b32_e32 v91, 0
	v_mov_b32_e32 v92, 0
	v_mov_b32_e32 v93, 0
	v_mov_b32_e32 v94, 0
	v_mov_b32_e32 v95, 0
	v_mov_b32_e32 v96, 0
	v_mov_b32_e32 v97, 0
	v_mov_b32_e32 v98, 0
	v_mov_b32_e32 v99, 0
	s_or_b64 s[28:29], s[44:45], s[64:65]
	v_add_u32_e32 v37, s23, v193
	v_mad_i64_i32 v[38:39], s[18:19], v37, s36, v[48:49]
	s_and_saveexec_b64 s[34:35], s[28:29]
	global_load_dwordx4 v[64:67], v[38:39], off offset:1024
	global_load_dwordx4 v[68:71], v[38:39], off offset:1280
	s_or_b64 exec, exec, s[34:35]
	s_or_b64 s[28:29], s[44:45], s[84:85]
	v_add_u32_e32 v37, s23, v195
	v_mad_i64_i32 v[40:41], s[18:19], v37, s36, v[48:49]
	s_and_saveexec_b64 s[34:35], s[28:29]
	global_load_dwordx4 v[76:79], v[40:41], off offset:1024
	global_load_dwordx4 v[80:83], v[40:41], off offset:1280
	s_or_b64 exec, exec, s[34:35]
	s_or_b64 s[28:29], s[44:45], s[90:91]
	v_add_u32_e32 v37, s23, v203
	v_mad_i64_i32 v[42:43], s[18:19], v37, s36, v[48:49]
	s_and_saveexec_b64 s[34:35], s[28:29]
	global_load_dwordx4 v[84:87], v[42:43], off offset:1024
	global_load_dwordx4 v[88:91], v[42:43], off offset:1280
	s_or_b64 exec, exec, s[34:35]
	s_or_b64 s[28:29], s[44:45], s[92:93]
	v_add_u32_e32 v37, s23, v205
	v_mad_i64_i32 v[44:45], s[18:19], v37, s36, v[48:49]
	s_and_saveexec_b64 s[34:35], s[28:29]
	global_load_dwordx4 v[92:95], v[44:45], off offset:1024
	global_load_dwordx4 v[96:99], v[44:45], off offset:1280
	s_or_b64 exec, exec, s[34:35]
	v_and_b32_e32 v3, 64, v235
	v_add_u32_e32 v3, 64, v3
	v_xor_b32_e32 v37, 1, v235
	v_cmp_lt_i32_e32 vcc, v37, v3
	s_nop 1
	v_cndmask_b32_e32 v37, v235, v37, vcc
	v_lshlrev_b32_e32 v47, 2, v37
	v_xor_b32_e32 v37, 2, v235
	v_cmp_lt_i32_e32 vcc, v37, v3
	s_nop 1
	v_cndmask_b32_e32 v37, v235, v37, vcc
	v_lshlrev_b32_e32 v50, 2, v37
	v_xor_b32_e32 v37, 4, v235
	v_cmp_lt_i32_e32 vcc, v37, v3
	s_nop 1
	v_cndmask_b32_e32 v37, v235, v37, vcc
	v_lshlrev_b32_e32 v51, 2, v37
	s_waitcnt vmcnt(6)
	v_lshlrev_b32_e32 v56, 16, v64
	v_and_b32_e32 v57, 0xffff0000, v64
	v_lshlrev_b32_e32 v59, 16, v65
	v_and_b32_e32 v58, 0xffff0000, v65
	v_lshlrev_b32_e32 v61, 16, v66
	v_and_b32_e32 v60, 0xffff0000, v66
	v_lshlrev_b32_e32 v63, 16, v67
	v_and_b32_e32 v62, 0xffff0000, v67
	v_mul_f32_e32 v52, v56, v56
	v_mul_f32_e32 v37, v57, v57
	v_add_f32_e32 v52, v52, v37
	v_mul_f32_e32 v37, v59, v59
	v_add_f32_e32 v52, v37, v52
	v_mul_f32_e32 v37, v58, v58
	v_add_f32_e32 v52, v37, v52
	v_mul_f32_e32 v37, v61, v61
	v_add_f32_e32 v52, v37, v52
	v_mul_f32_e32 v37, v60, v60
	v_add_f32_e32 v52, v37, v52
	v_mul_f32_e32 v37, v63, v63
	v_add_f32_e32 v52, v37, v52
	v_mul_f32_e32 v37, v62, v62
	v_add_f32_e32 v52, v37, v52
	s_waitcnt vmcnt(4)
	v_lshlrev_b32_e32 v56, 16, v76
	v_and_b32_e32 v57, 0xffff0000, v76
	v_lshlrev_b32_e32 v59, 16, v77
	v_and_b32_e32 v58, 0xffff0000, v77
	v_lshlrev_b32_e32 v61, 16, v78
	v_and_b32_e32 v60, 0xffff0000, v78
	v_lshlrev_b32_e32 v63, 16, v79
	v_and_b32_e32 v62, 0xffff0000, v79
	v_mul_f32_e32 v53, v56, v56
	v_mul_f32_e32 v37, v57, v57
	v_add_f32_e32 v53, v53, v37
	v_mul_f32_e32 v37, v59, v59
	v_add_f32_e32 v53, v37, v53
	v_mul_f32_e32 v37, v58, v58
	v_add_f32_e32 v53, v37, v53
	v_mul_f32_e32 v37, v61, v61
	v_add_f32_e32 v53, v37, v53
	v_mul_f32_e32 v37, v60, v60
	v_add_f32_e32 v53, v37, v53
	v_mul_f32_e32 v37, v63, v63
	v_add_f32_e32 v53, v37, v53
	v_mul_f32_e32 v37, v62, v62
	v_add_f32_e32 v53, v37, v53
	s_waitcnt vmcnt(2)
; __device__ __forceinline__ unsigned cvt_pk_bf16(float lo, float hi) { unsigned r; asm volatile("v_cvt_pk_bf16_f32 %0, %1, %2" : "=v"(r) : "v"(lo), "v"(hi)); return r; }
; __device__ __forceinline__ float bflo(unsigned u) { return __uint_as_float(u << 16); }
; __device__ __forceinline__ float bfhi(unsigned u) { return __uint_as_float(u & 0xffff0000u); }
; #define LAS __attribute__((address_space(3)))
; __device__ __forceinline__ void attn_item(LAS unsigned char* lds, const bf16* P, bf16* Y, const float* qg, const float* kg, const float* sinks, int item, int tid) {
;     ...
;         float kf[8];
; #pragma unroll
;         for (int e = 0; e < 4; ++e) { kf[2 * e] = bflo(kr[e]); kf[2 * e + 1] = bfhi(kr[e]); }
;         float ss = 0.f;
; #pragma unroll
;         for (int e = 0; e < 8; ++e) ss += kf[e] * kf[e];
;         ss += __shfl_xor(ss, 1); ss += __shfl_xor(ss, 2); ss += __shfl_xor(ss, 4);
;         const float rs = rsqrtf(ss * (1.f / 64.f) + EPS);
;         const f32x4 g0 = *(const f32x4*)(kg + 8 * c), g1 = *(const f32x4*)(kg + 8 * c + 4);
;         v4u kw; kw.x = cvt_pk_bf16(kf[0] * rs * g0.x, kf[1] * rs * g0.y); kw.y = cvt_pk_bf16(kf[2] * rs * g0.z, kf[3] * rs * g0.w);
;         kw.z = cvt_pk_bf16(kf[4] * rs * g1.x, kf[5] * rs * g1.y); kw.w = cvt_pk_bf16(kf[6] * rs * g1.z, kf[7] * rs * g1.w);
;         *(LAS v4u*)(Ks + key * 72 + 8 * c) = kw;
; #pragma unroll
;         for (int e = 0; e < 4; ++e) { Vt[(8 * c + 2 * e) * 264 + key] = (bf16)(vr[e] & 0xffffu); Vt[(8 * c + 2 * e + 1) * 264 + key] = (bf16)(vr[e] >> 16); }
	v_lshlrev_b32_e32 v56, 16, v84
	v_and_b32_e32 v57, 0xffff0000, v84
	v_lshlrev_b32_e32 v59, 16, v85
	v_and_b32_e32 v58, 0xffff0000, v85
	v_lshlrev_b32_e32 v61, 16, v86
	v_and_b32_e32 v60, 0xffff0000, v86
	v_lshlrev_b32_e32 v63, 16, v87
	v_and_b32_e32 v62, 0xffff0000, v87
	v_mul_f32_e32 v54, v56, v56
	v_mul_f32_e32 v37, v57, v57
	v_add_f32_e32 v54, v54, v37
	v_mul_f32_e32 v37, v59, v59
	v_add_f32_e32 v54, v37, v54
	v_mul_f32_e32 v37, v58, v58
	v_add_f32_e32 v54, v37, v54
	v_mul_f32_e32 v37, v61, v61
	v_add_f32_e32 v54, v37, v54
	v_mul_f32_e32 v37, v60, v60
	v_add_f32_e32 v54, v37, v54
	v_mul_f32_e32 v37, v63, v63
	v_add_f32_e32 v54, v37, v54
	v_mul_f32_e32 v37, v62, v62
	v_add_f32_e32 v54, v37, v54
	s_waitcnt vmcnt(0)
	v_lshlrev_b32_e32 v56, 16, v92
	v_and_b32_e32 v57, 0xffff0000, v92
	v_lshlrev_b32_e32 v59, 16, v93
	v_and_b32_e32 v58, 0xffff0000, v93
	v_lshlrev_b32_e32 v61, 16, v94
	v_and_b32_e32 v60, 0xffff0000, v94
	v_lshlrev_b32_e32 v63, 16, v95
	v_and_b32_e32 v62, 0xffff0000, v95
	v_mul_f32_e32 v55, v56, v56
	v_mul_f32_e32 v37, v57, v57
	v_add_f32_e32 v55, v55, v37
	v_mul_f32_e32 v37, v59, v59
	v_add_f32_e32 v55, v37, v55
	v_mul_f32_e32 v37, v58, v58
	v_add_f32_e32 v55, v37, v55
	v_mul_f32_e32 v37, v61, v61
	v_add_f32_e32 v55, v37, v55
	v_mul_f32_e32 v37, v60, v60
	v_add_f32_e32 v55, v37, v55
	v_mul_f32_e32 v37, v63, v63
	v_add_f32_e32 v55, v37, v55
	v_mul_f32_e32 v37, v62, v62
	v_add_f32_e32 v55, v37, v55
	ds_bpermute_b32 v40, v47, v52
	ds_bpermute_b32 v41, v47, v53
	ds_bpermute_b32 v42, v47, v54
	ds_bpermute_b32 v43, v47, v55
	s_waitcnt lgkmcnt(0)
	v_add_f32_e32 v52, v52, v40
	v_add_f32_e32 v53, v53, v41
	v_add_f32_e32 v54, v54, v42
	v_add_f32_e32 v55, v55, v43
	ds_bpermute_b32 v40, v50, v52
	ds_bpermute_b32 v41, v50, v53
	ds_bpermute_b32 v42, v50, v54
	ds_bpermute_b32 v43, v50, v55
	s_waitcnt lgkmcnt(0)
	v_add_f32_e32 v52, v52, v40
	v_add_f32_e32 v53, v53, v41
	v_add_f32_e32 v54, v54, v42
	v_add_f32_e32 v55, v55, v43
	ds_bpermute_b32 v40, v51, v52
	ds_bpermute_b32 v41, v51, v53
	ds_bpermute_b32 v42, v51, v54
	ds_bpermute_b32 v43, v51, v55
	s_waitcnt lgkmcnt(0)
	v_add_f32_e32 v52, v52, v40
	v_add_f32_e32 v53, v53, v41
	v_add_f32_e32 v54, v54, v42
	v_add_f32_e32 v55, v55, v43
	v_fmamk_f32 v52, v52, 0x3c800000, v196
	v_cmp_gt_f32_e32 vcc, s13, v52
	v_mul_f32_e32 v37, 0x4b800000, v52
	s_nop 0
	v_cndmask_b32_e32 v52, v52, v37, vcc
	v_rsq_f32_e32 v52, v52
	s_nop 0
	v_mul_f32_e32 v37, 0x45800000, v52
	v_cndmask_b32_e32 v52, v52, v37, vcc
	v_fmamk_f32 v53, v53, 0x3c800000, v196
	v_cmp_gt_f32_e32 vcc, s13, v53
	v_mul_f32_e32 v37, 0x4b800000, v53
	s_nop 0
	v_cndmask_b32_e32 v53, v53, v37, vcc
	v_rsq_f32_e32 v53, v53
	s_nop 0
	v_mul_f32_e32 v37, 0x45800000, v53
	v_cndmask_b32_e32 v53, v53, v37, vcc
	v_fmamk_f32 v54, v54, 0x3c800000, v196
	v_cmp_gt_f32_e32 vcc, s13, v54
	v_mul_f32_e32 v37, 0x4b800000, v54
	s_nop 0
	v_cndmask_b32_e32 v54, v54, v37, vcc
	v_rsq_f32_e32 v54, v54
	s_nop 0
	v_mul_f32_e32 v37, 0x45800000, v54
	v_cndmask_b32_e32 v54, v54, v37, vcc
	v_fmamk_f32 v55, v55, 0x3c800000, v196
	v_cmp_gt_f32_e32 vcc, s13, v55
	v_mul_f32_e32 v37, 0x4b800000, v55
	s_nop 0
	v_cndmask_b32_e32 v55, v55, v37, vcc
	v_rsq_f32_e32 v55, v55
	s_nop 0
	v_mul_f32_e32 v37, 0x45800000, v55
	v_cndmask_b32_e32 v55, v55, v37, vcc
	v_lshlrev_b32_e32 v56, 16, v64
	v_and_b32_e32 v57, 0xffff0000, v64
	v_lshlrev_b32_e32 v59, 16, v65
	v_and_b32_e32 v58, 0xffff0000, v65
	v_lshlrev_b32_e32 v61, 16, v66
	v_and_b32_e32 v60, 0xffff0000, v66
	v_lshlrev_b32_e32 v63, 16, v67
	v_and_b32_e32 v62, 0xffff0000, v67
	v_mul_f32_e32 v56, v52, v56
	v_mul_f32_e32 v56, v164, v56
	v_mul_f32_e32 v57, v52, v57
	v_mul_f32_e32 v57, v165, v57
	v_mul_f32_e32 v59, v52, v59
	v_mul_f32_e32 v59, v166, v59
	v_mul_f32_e32 v58, v52, v58
	v_mul_f32_e32 v58, v167, v58
	v_mul_f32_e32 v61, v52, v61
	v_mul_f32_e32 v61, v160, v61
	v_mul_f32_e32 v60, v52, v60
	v_mul_f32_e32 v60, v161, v60
	v_mul_f32_e32 v63, v52, v63
	v_mul_f32_e32 v63, v162, v63
	v_mul_f32_e32 v62, v52, v62
	v_mul_f32_e32 v62, v163, v62
	v_cvt_pk_bf16_f32 v40, v56, v57
	v_cvt_pk_bf16_f32 v41, v59, v58
	v_cvt_pk_bf16_f32 v42, v61, v60
	v_cvt_pk_bf16_f32 v43, v63, v62
	ds_write_b128 v219, v[40:43]
	ds_write_b16 v194, v68 offset:36864
	ds_write_b16_d16_hi v194, v68 offset:37392
	ds_write_b16 v194, v69 offset:37920
	ds_write_b16_d16_hi v194, v69 offset:38448
	ds_write_b16 v194, v70 offset:38976
	ds_write_b16_d16_hi v194, v70 offset:39504
	ds_write_b16 v194, v71 offset:40032
	ds_write_b16_d16_hi v194, v71 offset:40560
	v_lshlrev_b32_e32 v56, 16, v76
	v_and_b32_e32 v57, 0xffff0000, v76
	v_lshlrev_b32_e32 v59, 16, v77
	v_and_b32_e32 v58, 0xffff0000, v77
	v_lshlrev_b32_e32 v61, 16, v78
	v_and_b32_e32 v60, 0xffff0000, v78
	v_lshlrev_b32_e32 v63, 16, v79
	v_and_b32_e32 v62, 0xffff0000, v79
	v_mul_f32_e32 v56, v53, v56
	v_mul_f32_e32 v56, v164, v56
	v_mul_f32_e32 v57, v53, v57
	v_mul_f32_e32 v57, v165, v57
	v_mul_f32_e32 v59, v53, v59
	v_mul_f32_e32 v59, v166, v59
	v_mul_f32_e32 v58, v53, v58
	v_mul_f32_e32 v58, v167, v58
	v_mul_f32_e32 v61, v53, v61
	v_mul_f32_e32 v61, v160, v61
	v_mul_f32_e32 v60, v53, v60
	v_mul_f32_e32 v60, v161, v60
	v_mul_f32_e32 v63, v53, v63
	v_mul_f32_e32 v63, v162, v63
	v_mul_f32_e32 v62, v53, v62
	v_mul_f32_e32 v62, v163, v62
	v_cvt_pk_bf16_f32 v40, v56, v57
	v_cvt_pk_bf16_f32 v41, v59, v58
	v_cvt_pk_bf16_f32 v42, v61, v60
	v_cvt_pk_bf16_f32 v43, v63, v62
	ds_write_b128 v220, v[40:43]
	ds_write_b16 v202, v80 offset:36864
	ds_write_b16_d16_hi v202, v80 offset:37392
	ds_write_b16 v202, v81 offset:37920
	ds_write_b16_d16_hi v202, v81 offset:38448
	ds_write_b16 v202, v82 offset:38976
	ds_write_b16_d16_hi v202, v82 offset:39504
; #define LAS __attribute__((address_space(3)))
; __device__ __forceinline__ void attn_item(LAS unsigned char* lds, const bf16* P, bf16* Y, const float* qg, const float* kg, const float* sinks, int item, int tid) {
;     ...
;         *(LAS v4u*)(Ks + key * 72 + 8 * c) = kw;
; #pragma unroll
;         for (int e = 0; e < 4; ++e) { Vt[(8 * c + 2 * e) * 264 + key] = (bf16)(vr[e] & 0xffffu); Vt[(8 * c + 2 * e + 1) * 264 + key] = (bf16)(vr[e] >> 16); }
;     }
;     __syncthreads();
;     const int w = tid >> 6, lane = tid & 63, fr = lane & 15, fq = lane >> 4, g = w >> 1, h = hkv * 4 + g, half = w & 1;
;     const float slope2 = exp2f(-(float)(h + 1)) * LOG2E, sink2 = sinks[h] * LOG2E;
;     f32x4 qgv[4];
; #pragma unroll
;     for (int ks = 0; ks < 2; ++ks) { qgv[2 * ks] = *(const f32x4*)(qg + 32 * ks + 8 * fq); qgv[2 * ks + 1] = *(const f32x4*)(qg + 32 * ks + 8 * fq + 4); }
;     const int d0i = fr + 128 - 4 * fq; const float t0 = -slope2 * (float)d0i;
;     float be[2][4];
; #pragma unroll
;     for (int r = 0; r < 4; ++r) { const int da = d0i - r, db8 = d0i - 128 - r; be[0][r] = (da < 128) ? -slope2 * (float)da : -1e30f; be[1][r] = (db8 >= 0) ? -slope2 * (float)db8 : -1e30f; }
	ds_write_b16 v202, v83 offset:40032
	ds_write_b16_d16_hi v202, v83 offset:40560
	v_lshlrev_b32_e32 v56, 16, v84
	v_and_b32_e32 v57, 0xffff0000, v84
	v_lshlrev_b32_e32 v59, 16, v85
	v_and_b32_e32 v58, 0xffff0000, v85
	v_lshlrev_b32_e32 v61, 16, v86
	v_and_b32_e32 v60, 0xffff0000, v86
	v_lshlrev_b32_e32 v63, 16, v87
	v_and_b32_e32 v62, 0xffff0000, v87
	v_mul_f32_e32 v56, v54, v56
	v_mul_f32_e32 v56, v164, v56
	v_mul_f32_e32 v57, v54, v57
	v_mul_f32_e32 v57, v165, v57
	v_mul_f32_e32 v59, v54, v59
	v_mul_f32_e32 v59, v166, v59
	v_mul_f32_e32 v58, v54, v58
	v_mul_f32_e32 v58, v167, v58
	v_mul_f32_e32 v61, v54, v61
	v_mul_f32_e32 v61, v160, v61
	v_mul_f32_e32 v60, v54, v60
	v_mul_f32_e32 v60, v161, v60
	v_mul_f32_e32 v63, v54, v63
	v_mul_f32_e32 v63, v162, v63
	v_mul_f32_e32 v62, v54, v62
	v_mul_f32_e32 v62, v163, v62
	v_cvt_pk_bf16_f32 v40, v56, v57
	v_cvt_pk_bf16_f32 v41, v59, v58
	v_cvt_pk_bf16_f32 v42, v61, v60
	v_cvt_pk_bf16_f32 v43, v63, v62
	ds_write_b128 v221, v[40:43]
	ds_write_b16 v204, v88 offset:36864
	ds_write_b16_d16_hi v204, v88 offset:37392
	ds_write_b16 v204, v89 offset:37920
	ds_write_b16_d16_hi v204, v89 offset:38448
	ds_write_b16 v204, v90 offset:38976
	ds_write_b16_d16_hi v204, v90 offset:39504
	ds_write_b16 v204, v91 offset:40032
	ds_write_b16_d16_hi v204, v91 offset:40560
	v_lshlrev_b32_e32 v56, 16, v92
	v_and_b32_e32 v57, 0xffff0000, v92
	v_lshlrev_b32_e32 v59, 16, v93
	v_and_b32_e32 v58, 0xffff0000, v93
	v_lshlrev_b32_e32 v61, 16, v94
	v_and_b32_e32 v60, 0xffff0000, v94
	v_lshlrev_b32_e32 v63, 16, v95
	v_and_b32_e32 v62, 0xffff0000, v95
	v_mul_f32_e32 v56, v55, v56
	v_mul_f32_e32 v56, v164, v56
	v_mul_f32_e32 v57, v55, v57
	v_mul_f32_e32 v57, v165, v57
	v_mul_f32_e32 v59, v55, v59
	v_mul_f32_e32 v59, v166, v59
	v_mul_f32_e32 v58, v55, v58
	v_mul_f32_e32 v58, v167, v58
	v_mul_f32_e32 v61, v55, v61
	v_mul_f32_e32 v61, v160, v61
	v_mul_f32_e32 v60, v55, v60
	v_mul_f32_e32 v60, v161, v60
	v_mul_f32_e32 v63, v55, v63
	v_mul_f32_e32 v63, v162, v63
	v_mul_f32_e32 v62, v55, v62
	v_mul_f32_e32 v62, v163, v62
	v_cvt_pk_bf16_f32 v40, v56, v57
	v_cvt_pk_bf16_f32 v41, v59, v58
	v_cvt_pk_bf16_f32 v42, v61, v60
	v_cvt_pk_bf16_f32 v43, v63, v62
	ds_write_b128 v222, v[40:43]
	ds_write_b16 v206, v96 offset:36864
	ds_write_b16_d16_hi v206, v96 offset:37392
	ds_write_b16 v206, v97 offset:37920
	ds_write_b16_d16_hi v206, v97 offset:38448
	ds_write_b16 v206, v98 offset:38976
	ds_write_b16_d16_hi v206, v98 offset:39504
	ds_write_b16 v206, v99 offset:40032
	ds_write_b16_d16_hi v206, v99 offset:40560
	s_and_b32 s18, s24, 0xfffff800
	v_or_b32_e32 v44, s18, v191
	s_and_b32 s18, s22, 0x780
	v_or_b32_e32 v72, s18, v44
	s_mov_b32 s2, 0
	s_mov_b32 s18, 0x42fc0000
	s_cmp_eq_u32 s3, 0
	s_cselect_b64 s[62:63], -1, 0
	v_lshl_add_u64 v[74:75], v[0:1], 1, v[110:111]
	v_mov_b32_e32 v0, v218
	v_mov_b32_e32 v133, v215
	v_add_u32_e32 v36, 1, v46
	v_cvt_f32_i32_e32 v36, v36
	v_mov_b32_e32 v37, 0x42800000
	v_ashrrev_i32_e32 v47, 31, v46
	v_cmp_lt_f32_e32 vcc, s18, v36
	s_waitcnt lgkmcnt(0)
	s_barrier
	v_cndmask_b32_e32 v37, 0, v37, vcc
	v_sub_f32_e32 v36, v37, v36
	v_exp_f32_e32 v36, v36
	v_not_b32_e32 v37, 63
	v_cndmask_b32_e32 v37, 0, v37, vcc
	v_ldexp_f32 v52, v36, v37
	v_mov_b32_e32 v53, v184
	v_mov_b32_e32 v36, v168
	v_mov_b32_e32 v37, v169
	v_mov_b32_e32 v38, v170
	v_mov_b32_e32 v39, v171
	v_mov_b32_e32 v40, v172
	v_mov_b32_e32 v41, v173
	v_mov_b32_e32 v42, v174
	v_mov_b32_e32 v43, v175
	v_mov_b32_e32 v44, v176
	v_mov_b32_e32 v45, v177
	v_mov_b32_e32 v46, v178
	v_mov_b32_e32 v47, v179
	v_mov_b32_e32 v48, v180
	v_mov_b32_e32 v49, v181
	v_mov_b32_e32 v50, v182
	v_mov_b32_e32 v51, v183
	v_mul_f32_e32 v52, 0xbfb8aa3b, v52
	v_mul_f32_e32 v54, v208, v52
	v_cndmask_b32_e64 v78, v236, v54, s[48:49]
	v_mul_f32_e32 v54, v209, v52
	v_cndmask_b32_e64 v79, v236, v54, s[50:51]
	v_mul_f32_e32 v54, v210, v52
	v_cndmask_b32_e64 v80, v236, v54, s[52:53]
	v_mul_f32_e32 v54, v211, v52
	v_cndmask_b32_e64 v81, v236, v54, s[54:55]
	v_mul_f32_e32 v54, v212, v52
	v_cndmask_b32_e64 v82, v236, v54, s[56:57]
	v_mul_f32_e32 v54, v213, v52
	v_mul_f32_e32 v76, v207, v52
	v_cndmask_b32_e64 v83, v236, v54, s[58:59]
	v_mul_f32_e32 v54, v214, v52
	v_cndmask_b32_e64 v77, v236, v76, s[46:47]
	v_cndmask_b32_e64 v84, v236, v54, s[60:61]
	v_fmamk_f32 v88, v52, 0xc1800000, v76
	v_fmamk_f32 v89, v52, 0xc1880000, v76
	v_fmamk_f32 v90, v52, 0xc1900000, v76
	v_fmamk_f32 v91, v52, 0xc1980000, v76
	v_fmamk_f32 v92, v52, 0xc2000000, v76
	v_fmamk_f32 v93, v52, 0xc2040000, v76
	v_fmamk_f32 v94, v52, 0xc2080000, v76
	v_fmamk_f32 v95, v52, 0xc20c0000, v76
	v_fmamk_f32 v96, v52, 0xc2400000, v76
	v_fmamk_f32 v97, v52, 0xc2440000, v76
	v_fmamk_f32 v98, v52, 0xc2480000, v76
	v_fmamk_f32 v99, v52, 0xc24c0000, v76
	v_fmamk_f32 v113, v52, 0xc2800000, v76
	v_fmamk_f32 v115, v52, 0xc2820000, v76
	v_fmamk_f32 v117, v52, 0xc2840000, v76
	v_fmamk_f32 v119, v52, 0xc2860000, v76
	v_fmamk_f32 v121, v52, 0xc2a00000, v76
	v_fmamk_f32 v123, v52, 0xc2a20000, v76
	v_fmamk_f32 v124, v52, 0xc2a40000, v76
	v_fmamk_f32 v125, v52, 0xc2a60000, v76
	v_fmamk_f32 v126, v52, 0xc2c00000, v76
	v_fmamk_f32 v127, v52, 0xc2c20000, v76
	v_fmamk_f32 v128, v52, 0xc2c40000, v76
	v_fmamk_f32 v129, v52, 0xc2c60000, v76
	v_fmamk_f32 v130, v52, 0xc2e00000, v76
	v_fmamk_f32 v131, v52, 0xc2e20000, v76
	v_fmamk_f32 v132, v52, 0xc2e40000, v76
	v_fmac_f32_e32 v76, 0xc2e60000, v52
	v_mul_f32_e32 v85, 0x3fb8aa3b, v53
	v_xor_b32_e32 v53, 16, v235
	v_cmp_lt_i32_e32 vcc, v53, v3
	s_nop 1
	v_cndmask_b32_e32 v53, v235, v53, vcc
	v_lshlrev_b32_e32 v86, 2, v53
	v_xor_b32_e32 v53, 32, v235
	v_cmp_lt_i32_e32 vcc, v53, v3
	s_nop 1
	v_cndmask_b32_e32 v3, v235, v53, vcc
	v_lshlrev_b32_e32 v87, 2, v3
